# attention loops: v_pk_add_f32 row-sum adds split into scalar v_add_f32 pairs
# baseline (speedup 1.0000x reference)
.LBB0_626:
	s_lshl_b32 s2, s9, 14
	s_add_i32 s2, s58, s2
	v_lshl_add_u64 v[2:3], s[60:61], 0, v[0:1]
	v_lshl_add_u64 v[2:3], v[2:3], 0, s[96:97]
	s_mov_b32 m0, s2
	v_mov_b32_e32 v15, v1
	global_load_lds_dwordx4 v[2:3], off
	v_lshl_add_u64 v[2:3], s[60:61], 0, v[14:15]
	v_lshl_add_u64 v[2:3], v[2:3], 0, s[96:97]
	s_add_i32 m0, s2, 0x2000
	s_cmp_lt_u32 s27, s59
	global_load_lds_dwordx4 v[2:3], off
	s_cselect_b64 vcc, -1, 0
	v_add_u32_e32 v2, 0x30000, v0
	v_add_u32_e32 v3, 0x30000, v14
	s_cmp_lg_u64 vcc, 0
	v_cndmask_b32_e32 v14, v14, v3, vcc
	v_cndmask_b32_e32 v0, v0, v2, vcc
	s_addc_u32 s27, s27, 0
	s_mul_i32 s2, s12, 0x6000
	v_add_u32_e32 v15, s2, v236
	v_add_u32_e32 v6, v15, v241
	ds_read_b128 v[2:5], v6
	ds_read_b128 v[6:9], v6 offset:12288
	v_exp_f32_e32 v12, v96
	s_waitcnt lgkmcnt(0)
	v_mfma_f32_32x32x16_bf16 v[112:127], v[2:5], v[144:147], 0
	v_mov_b32_e32 v2, v97
	v_exp_f32_e32 v96, v98
	v_exp_f32_e32 v97, v99
	v_exp_f32_e32 v13, v2
	v_mfma_f32_32x32x16_bf16 v[128:143], v[6:9], v[144:147], 0
	v_add_u32_e32 v2, v15, v242
	ds_read_b128 v[4:7], v2
	ds_read_b128 v[8:11], v2 offset:12288
	v_mov_b32_e32 v2, v100
	v_mov_b32_e32 v3, v101
	v_exp_f32_e32 v98, v2
	v_exp_f32_e32 v99, v3
	v_exp_f32_e32 v100, v102
	v_exp_f32_e32 v101, v103
	v_cvt_pk_bf16_f32 v2, v12, v13
	s_waitcnt lgkmcnt(0)
	v_mfma_f32_32x32x16_bf16 v[112:127], v[4:7], v[148:151], v[112:127]
	v_cvt_pk_bf16_f32 v3, v96, v97
	v_cvt_pk_bf16_f32 v4, v98, v99
	v_cvt_pk_bf16_f32 v5, v100, v101
	s_nop 0
	v_permlane32_swap_b32_e32 v2, v4
	v_permlane32_swap_b32_e32 v3, v5
	v_mfma_f32_32x32x16_bf16 v[128:143], v[8:11], v[148:151], v[128:143]
	v_add_u32_e32 v10, v15, v243
	ds_read_b128 v[6:9], v10
	v_add_f32_e64 v102, v214, v12
	v_add_f32_e64 v103, v215, v13
	ds_read_b128 v[10:13], v10 offset:12288
	v_exp_f32_e32 v104, v104
	v_exp_f32_e32 v105, v105
	s_waitcnt lgkmcnt(0)
	v_mfma_f32_32x32x16_bf16 v[112:127], v[6:9], v[152:155], v[112:127]
	v_add_f32_e64 v6, v96, v102
	v_add_f32_e64 v7, v97, v103
	v_exp_f32_e32 v102, v106
	v_exp_f32_e32 v103, v107
	v_add_f32_e32 v6, v98, v6
	v_add_f32_e32 v7, v99, v7
	s_nop 0
	v_add_f32_e32 v6, v100, v6
	v_add_f32_e32 v7, v101, v7
	s_nop 0
	v_add_f32_e32 v100, v104, v6
	v_add_f32_e32 v101, v105, v7
	v_mfma_f32_32x32x16_bf16 v[128:143], v[10:13], v[152:155], v[128:143]
	v_add_u32_e32 v6, v15, v244
	ds_read_b128 v[8:11], v6
	ds_read_b128 v[96:99], v6 offset:12288
	v_exp_f32_e32 v106, v108
	v_exp_f32_e32 v107, v109
	v_exp_f32_e32 v108, v110
	v_exp_f32_e32 v109, v111
	v_cvt_pk_bf16_f32 v6, v104, v105
	s_waitcnt lgkmcnt(0)
	v_mfma_f32_32x32x16_bf16 v[112:127], v[8:11], v[156:159], v[112:127]
	v_cvt_pk_bf16_f32 v7, v102, v103
	v_cvt_pk_bf16_f32 v8, v106, v107
	v_cvt_pk_bf16_f32 v9, v108, v109
	s_nop 0
	v_permlane32_swap_b32_e32 v6, v8
	v_permlane32_swap_b32_e32 v7, v9
	v_mfma_f32_32x32x16_bf16 v[128:143], v[96:99], v[156:159], v[128:143]
	v_add_u32_e32 v96, v15, v245
	ds_read_b128 v[10:13], v96
	ds_read_b128 v[96:99], v96 offset:12288
	v_exp_f32_e32 v104, v80
	s_waitcnt lgkmcnt(0)
	v_mfma_f32_32x32x16_bf16 v[112:127], v[10:13], v[160:163], v[112:127]
	v_exp_f32_e32 v105, v81
	v_exp_f32_e32 v110, v82
	v_exp_f32_e32 v111, v83
	v_mfma_f32_32x32x16_bf16 v[128:143], v[96:99], v[160:163], v[128:143]
	v_add_u32_e32 v80, v15, v246
	ds_read_b128 v[10:13], v80
	ds_read_b128 v[80:83], v80 offset:12288
	v_exp_f32_e32 v96, v84
	v_exp_f32_e32 v97, v85
	v_exp_f32_e32 v98, v86
	v_exp_f32_e32 v99, v87
	v_cvt_pk_bf16_f32 v192, v104, v105
	v_cvt_pk_bf16_f32 v193, v110, v111
	v_cvt_pk_bf16_f32 v194, v96, v97
	v_cvt_pk_bf16_f32 v195, v98, v99
	s_waitcnt lgkmcnt(0)
	v_mfma_f32_32x32x16_bf16 v[128:143], v[80:83], v[164:167], v[128:143]
	v_permlane32_swap_b32_e32 v192, v194
	v_permlane32_swap_b32_e32 v193, v195
	v_mfma_f32_32x32x16_bf16 v[112:127], v[10:13], v[164:167], v[112:127]
	v_add_u32_e32 v80, v15, v247
	ds_read_b128 v[10:13], v80
	ds_read_b128 v[80:83], v80 offset:12288
	s_waitcnt lgkmcnt(0)
	v_mfma_f32_32x32x16_bf16 v[112:127], v[10:13], v[168:171], v[112:127]
	v_exp_f32_e32 v10, v88
	v_exp_f32_e32 v11, v89
	v_exp_f32_e32 v12, v90
	v_exp_f32_e32 v13, v91
	v_mfma_f32_32x32x16_bf16 v[128:143], v[80:83], v[168:171], v[128:143]
	v_mov_b32_e32 v88, v92
	v_mov_b32_e32 v89, v93
	v_add_f32_e64 v92, v102, v100
	v_add_f32_e64 v93, v103, v101
	v_add_u32_e32 v84, v15, v248
	v_add_f32_e32 v92, v106, v92
	v_add_f32_e32 v93, v107, v93
	v_add_f32_e32 v92, v108, v92
	v_add_f32_e32 v93, v109, v93
	v_add_f32_e32 v92, v104, v92
	v_add_f32_e32 v93, v105, v93
	v_exp_f32_e32 v88, v88
	v_add_f32_e32 v92, v110, v92
	v_add_f32_e32 v93, v111, v93
	v_exp_f32_e32 v89, v89
	v_add_f32_e32 v92, v96, v92
	v_add_f32_e32 v93, v97, v93
	ds_read_b128 v[80:83], v84
	ds_read_b128 v[84:87], v84 offset:12288
	v_exp_f32_e32 v90, v94
	v_exp_f32_e32 v91, v95
	v_add_f32_e32 v92, v98, v92
	v_add_f32_e32 v93, v99, v93
	s_waitcnt lgkmcnt(0)
; #define SBAR() __builtin_amdgcn_sched_barrier(0)
; #define VSET(S, d0) do { constexpr int b_ = (d0) * 512; TRRD(S##l0, b_); TRRD(S##h0, b_ + 2048); TRRD(S##l1, b_ + 4096); TRRD(S##h1, b_ + 6144); \
;         TRRD(S##l2, b_ + 8192); TRRD(S##h2, b_ + 10240); TRRD(S##l3, b_ + 12288); TRRD(S##h3, b_ + 14336); } while (0)
; #define LWAIT(n) do { asm volatile("s_waitcnt lgkmcnt(" #n ")" ::: "memory"); SBAR(); } while (0)
; __device__ __forceinline__ void pv_tile(f32x16* o, unsigned vb, bf16x8 pa0, bf16x8 pa1, bf16x8 pa2, bf16x8 pa3) {
;     ...
;     s16x4 Al0, Al1, Al2, Al3, Ah0, Ah1, Ah2, Ah3, Bl0, Bl1, Bl2, Bl3, Bh0, Bh1, Bh2, Bh3;
;     VSET(A, 0);
;     VSET(B, 1); LWAIT(8); VMMA(A, 0); SBAR();
;     VSET(A, 2); LWAIT(8); VMMA(B, 1); SBAR();
;     VSET(B, 3); LWAIT(8); VMMA(A, 2); SBAR();
;     LWAIT(0); VMMA(B, 3);
	v_mfma_f32_32x32x16_bf16 v[128:143], v[84:87], v[172:175], v[128:143]
	v_add_f32_e64 v92, v10, v92
	v_add_f32_e64 v93, v11, v93
	v_cvt_pk_bf16_f32 v10, v10, v11
	v_add_f32_e64 v92, v12, v92
	v_add_f32_e64 v93, v13, v93
	v_cvt_pk_bf16_f32 v11, v12, v13
	v_add_f32_e32 v92, v88, v92
	v_add_f32_e32 v93, v89, v93
	v_cvt_pk_bf16_f32 v12, v88, v89
	v_add_f32_e32 v214, v90, v92
	v_add_f32_e32 v215, v91, v93
	v_cvt_pk_bf16_f32 v13, v90, v91
	v_permlane32_swap_b32_e32 v10, v12
	s_nop 0
	v_permlane32_swap_b32_e32 v11, v13
	v_mfma_f32_32x32x16_bf16 v[112:127], v[80:83], v[172:175], v[112:127]
	v_add_u32_e32 v92, v15, v249
	v_add_u32_e32 v93, v15, v250
	v_add_u32_e32 v94, v15, v251
	v_add_u32_e32 v95, v15, v252
	ds_read_b128 v[96:99], v92
	ds_read_b128 v[100:103], v93
	ds_read_b128 v[104:107], v94
	ds_read_b128 v[80:83], v92 offset:12288
	ds_read_b128 v[84:87], v93 offset:12288
	ds_read_b128 v[88:91], v94 offset:12288
	ds_read_b128 v[222:225], v95 offset:12288
	ds_read_b128 v[92:95], v95
	s_waitcnt lgkmcnt(7)
	v_mfma_f32_32x32x16_bf16 v[112:127], v[96:99], v[176:179], v[112:127]
	s_waitcnt lgkmcnt(6)
	v_mfma_f32_32x32x16_bf16 v[112:127], v[100:103], v[180:183], v[112:127]
	s_waitcnt lgkmcnt(5)
	v_mfma_f32_32x32x16_bf16 v[112:127], v[104:107], v[184:187], v[112:127]
	s_waitcnt lgkmcnt(0)
	v_mfma_f32_32x32x16_bf16 v[96:111], v[92:95], v[188:191], v[112:127]
	v_mfma_f32_32x32x16_bf16 v[128:143], v[80:83], v[176:179], v[128:143]
	v_mfma_f32_32x32x16_bf16 v[128:143], v[84:87], v[180:183], v[128:143]
	v_mfma_f32_32x32x16_bf16 v[128:143], v[88:91], v[184:187], v[128:143]
	v_mfma_f32_32x32x16_bf16 v[80:95], v[222:225], v[188:191], v[128:143]
	v_lshl_add_u32 v15, s7, 14, v237
	ds_read_b64_tr_b16 v[112:113], v15 offset:0
	ds_read_b64_tr_b16 v[114:115], v15 offset:0x800
	ds_read_b64_tr_b16 v[116:117], v15 offset:0x1000
	ds_read_b64_tr_b16 v[118:119], v15 offset:0x1800
	ds_read_b64_tr_b16 v[120:121], v15 offset:0x2000
	ds_read_b64_tr_b16 v[122:123], v15 offset:0x2800
	ds_read_b64_tr_b16 v[124:125], v15 offset:0x3000
	ds_read_b64_tr_b16 v[126:127], v15 offset:0x3800
	ds_read_b64_tr_b16 v[128:129], v15 offset:0x200
	ds_read_b64_tr_b16 v[130:131], v15 offset:0xa00
	ds_read_b64_tr_b16 v[132:133], v15 offset:0x1200
	ds_read_b64_tr_b16 v[134:135], v15 offset:0x1a00
	ds_read_b64_tr_b16 v[136:137], v15 offset:0x2200
	ds_read_b64_tr_b16 v[138:139], v15 offset:0x2a00
	ds_read_b64_tr_b16 v[140:141], v15 offset:0x3200
	ds_read_b64_tr_b16 v[142:143], v15 offset:0x3a00
	s_waitcnt lgkmcnt(8)
	s_nop 0
	v_mfma_f32_32x32x16_bf16 v[64:79], v[2:5], v[112:115], v[64:79]
	v_mfma_f32_32x32x16_bf16 v[64:79], v[6:9], v[116:119], v[64:79]
	v_mfma_f32_32x32x16_bf16 v[64:79], v[192:195], v[120:123], v[64:79]
	v_mfma_f32_32x32x16_bf16 v[64:79], v[10:13], v[124:127], v[64:79]
	ds_read_b64_tr_b16 v[112:113], v15 offset:0x400
	ds_read_b64_tr_b16 v[114:115], v15 offset:0xc00
	ds_read_b64_tr_b16 v[116:117], v15 offset:0x1400
	ds_read_b64_tr_b16 v[118:119], v15 offset:0x1c00
	ds_read_b64_tr_b16 v[120:121], v15 offset:0x2400
	ds_read_b64_tr_b16 v[122:123], v15 offset:0x2c00
	ds_read_b64_tr_b16 v[124:125], v15 offset:0x3400
	ds_read_b64_tr_b16 v[126:127], v15 offset:0x3c00
	s_waitcnt lgkmcnt(8)
	v_mfma_f32_32x32x16_bf16 v[48:63], v[2:5], v[128:131], v[48:63]
	v_mfma_f32_32x32x16_bf16 v[48:63], v[6:9], v[132:135], v[48:63]
	v_mfma_f32_32x32x16_bf16 v[48:63], v[192:195], v[136:139], v[48:63]
	v_mfma_f32_32x32x16_bf16 v[48:63], v[10:13], v[140:143], v[48:63]
	ds_read_b64_tr_b16 v[128:129], v15 offset:0x600
	ds_read_b64_tr_b16 v[130:131], v15 offset:0xe00
	ds_read_b64_tr_b16 v[132:133], v15 offset:0x1600
	ds_read_b64_tr_b16 v[134:135], v15 offset:0x1e00
	ds_read_b64_tr_b16 v[136:137], v15 offset:0x2600
	ds_read_b64_tr_b16 v[138:139], v15 offset:0x2e00
	ds_read_b64_tr_b16 v[140:141], v15 offset:0x3600
	ds_read_b64_tr_b16 v[142:143], v15 offset:0x3e00
	s_waitcnt lgkmcnt(8)
	v_mfma_f32_32x32x16_bf16 v[32:47], v[2:5], v[112:115], v[32:47]
	v_mfma_f32_32x32x16_bf16 v[32:47], v[6:9], v[116:119], v[32:47]
	v_mfma_f32_32x32x16_bf16 v[32:47], v[192:195], v[120:123], v[32:47]
	v_mfma_f32_32x32x16_bf16 v[32:47], v[10:13], v[124:127], v[32:47]
	s_waitcnt lgkmcnt(0)
	v_mfma_f32_32x32x16_bf16 v[16:31], v[2:5], v[128:131], v[16:31]
	s_waitcnt vmcnt(5)
	s_barrier
	s_add_i32 s13, s13, -1
	s_cmp_eq_u32 s13, 0
	v_mfma_f32_32x32x16_bf16 v[16:31], v[6:9], v[132:135], v[16:31]
	v_mfma_f32_32x32x16_bf16 v[16:31], v[192:195], v[136:139], v[16:31]
	v_mfma_f32_32x32x16_bf16 v[16:31], v[10:13], v[140:143], v[16:31]
	s_cbranch_scc1 .LBB0_629
	s_mov_b32 s2, s12
	s_mov_b32 s12, s9
	s_mov_b32 s9, s7
	s_branch .LBB0_624

.LBB0_821:
	s_mov_b32 s12, s14
	s_lshl_b32 s14, s2, 14
	s_mov_b32 s63, s70
	s_mov_b32 s70, s2
	s_add_i32 s2, s9, s14
	s_add_i32 m0, s2, 0xc000
	v_add_u32_e32 v0, 0x98000, v163
	global_load_lds_dwordx4 v165, s[60:61]
	s_add_i32 m0, s2, 0xe000
	s_cmp_lt_u32 s83, s57
	s_cselect_b64 s[18:19], -1, 0
	s_and_b64 s[34:35], s[18:19], exec
	s_cselect_b32 s2, 0x98000, 0
	s_cmp_lg_u64 s[18:19], 0
	global_load_lds_dwordx4 v164, s[60:61]
	v_add_u32_e32 v164, s2, v164
	v_add_u32_e32 v165, s2, v165
	s_addc_u32 s83, s83, 0
	s_lshl_b32 s2, s63, 14
	s_add_i32 s2, s9, s2
	s_mov_b32 m0, s2
	v_add_u32_e32 v98, 0x98000, v162
	global_load_lds_dwordx4 v163, s[76:77]
	s_add_i32 m0, s2, 0x2000
	s_cmp_lt_u32 s62, s57
	global_load_lds_dwordx4 v162, s[76:77]
	s_cselect_b64 vcc, -1, 0
	s_cmp_lg_u64 vcc, 0
	v_cndmask_b32_e32 v162, v162, v98, vcc
	v_cndmask_b32_e32 v163, v163, v0, vcc
	s_addc_u32 s62, s62, 0
	v_lshl_add_u32 v0, s12, 14, v160
	v_add_u32_e32 v102, v0, v166
	v_exp_f32_e32 v150, v82
	v_exp_f32_e32 v151, v83
	v_exp_f32_e32 v152, v84
	v_exp_f32_e32 v153, v85
	ds_read_b128 v[98:101], v102
	ds_read_b128 v[114:117], v102 offset:8192
	v_exp_f32_e32 v170, v86
	v_exp_f32_e32 v171, v87
	v_exp_f32_e32 v172, v88
	v_exp_f32_e32 v173, v89
	v_cvt_pk_bf16_f32 v146, v150, v151
	v_cvt_pk_bf16_f32 v147, v152, v153
	v_cvt_pk_bf16_f32 v148, v170, v171
	v_cvt_pk_bf16_f32 v149, v172, v173
	s_waitcnt lgkmcnt(0)
	v_mfma_f32_32x32x16_bf16 v[98:113], v[98:101], v[130:133], 0
	v_permlane32_swap_b32_e32 v146, v148
	v_permlane32_swap_b32_e32 v147, v149
	v_mfma_f32_32x32x16_bf16 v[114:129], v[114:117], v[130:133], 0
	v_add_u32_e32 v86, v0, v167
	v_mov_b32_e32 v174, v92
	v_mov_b32_e32 v175, v93
	ds_read_b128 v[82:85], v86
	ds_read_b128 v[86:89], v86 offset:8192
	v_exp_f32_e32 v90, v90
	v_exp_f32_e32 v91, v91
	v_add_f32_e32 v92, v156, v150
	v_add_f32_e32 v93, v157, v151
	v_exp_f32_e32 v156, v174
	v_exp_f32_e32 v157, v175
	v_exp_f32_e32 v174, v94
	v_exp_f32_e32 v175, v95
	v_exp_f32_e32 v176, v96
	v_exp_f32_e32 v177, v97
	v_add_f32_e32 v92, v152, v92
	v_add_f32_e32 v93, v153, v93
	v_cvt_pk_bf16_f32 v150, v90, v91
	v_add_f32_e32 v92, v170, v92
	v_add_f32_e32 v93, v171, v93
	v_cvt_pk_bf16_f32 v151, v156, v157
	v_add_f32_e32 v92, v172, v92
	v_add_f32_e32 v93, v173, v93
	v_cvt_pk_bf16_f32 v152, v174, v175
	v_add_f32_e32 v92, v90, v92
	v_add_f32_e32 v93, v91, v93
	v_cvt_pk_bf16_f32 v153, v176, v177
	s_waitcnt lgkmcnt(0)
	v_mfma_f32_32x32x16_bf16 v[114:129], v[86:89], v[134:137], v[114:129]
	v_permlane32_swap_b32_e32 v150, v152
	v_permlane32_swap_b32_e32 v151, v153
	v_mfma_f32_32x32x16_bf16 v[98:113], v[82:85], v[134:137], v[98:113]
	v_add_u32_e32 v86, v0, v168
	v_exp_f32_e32 v178, v66
	v_exp_f32_e32 v179, v67
	v_exp_f32_e32 v180, v68
	v_exp_f32_e32 v181, v69
	ds_read_b128 v[82:85], v86
	ds_read_b128 v[86:89], v86 offset:8192
	v_exp_f32_e32 v182, v70
	v_exp_f32_e32 v183, v71
	v_exp_f32_e32 v184, v72
	v_exp_f32_e32 v185, v73
	v_cvt_pk_bf16_f32 v170, v178, v179
	v_cvt_pk_bf16_f32 v171, v180, v181
	v_cvt_pk_bf16_f32 v172, v182, v183
	v_cvt_pk_bf16_f32 v173, v184, v185
	s_waitcnt lgkmcnt(0)
	v_mfma_f32_32x32x16_bf16 v[98:113], v[82:85], v[138:141], v[98:113]
	v_permlane32_swap_b32_e32 v170, v172
	v_permlane32_swap_b32_e32 v171, v173
	v_mfma_f32_32x32x16_bf16 v[114:129], v[86:89], v[138:141], v[114:129]
	v_add_u32_e32 v0, v0, v169
	v_add_f32_e64 v156, v156, v92
	v_add_f32_e64 v157, v157, v93
	ds_read_b128 v[232:235], v0
	ds_read_b128 v[236:239], v0 offset:8192
	v_mov_b32_e32 v193, v81
	v_add_f32_e32 v248, v174, v156
	v_add_f32_e32 v249, v175, v157
	v_exp_f32_e32 v240, v74
	v_add_f32_e32 v248, v176, v248
	v_add_f32_e32 v249, v177, v249
	v_exp_f32_e32 v241, v75
	v_add_f32_e32 v248, v178, v248
	v_add_f32_e32 v249, v179, v249
	s_waitcnt lgkmcnt(0)
; #define SBAR() __builtin_amdgcn_sched_barrier(0)
; #define VSET(S, d0) do { constexpr int b_ = (d0) * 512; TRRD(S##l0, b_); TRRD(S##h0, b_ + 2048); TRRD(S##l1, b_ + 4096); TRRD(S##h1, b_ + 6144); \
;         TRRD(S##l2, b_ + 8192); TRRD(S##h2, b_ + 10240); TRRD(S##l3, b_ + 12288); TRRD(S##h3, b_ + 14336); } while (0)
; #define LWAIT(n) do { asm volatile("s_waitcnt lgkmcnt(" #n ")" ::: "memory"); SBAR(); } while (0)
; __device__ __forceinline__ void pv_tile(f32x16* o, unsigned vb, bf16x8 pa0, bf16x8 pa1, bf16x8 pa2, bf16x8 pa3) {
;     ...
;     s16x4 Al0, Al1, Al2, Al3, Ah0, Ah1, Ah2, Ah3, Bl0, Bl1, Bl2, Bl3, Bh0, Bh1, Bh2, Bh3;
;     VSET(A, 0);
;     VSET(B, 1); LWAIT(8); VMMA(A, 0); SBAR();
;     VSET(A, 2); LWAIT(8); VMMA(B, 1); SBAR();
;     VSET(B, 3); LWAIT(8); VMMA(A, 2); SBAR();
;     LWAIT(0); VMMA(B, 3);
	v_mfma_f32_32x32x16_bf16 v[82:97], v[232:235], v[142:145], v[98:113]
	v_exp_f32_e32 v242, v76
	v_exp_f32_e32 v243, v77
	v_add_f32_e32 v250, v180, v248
	v_add_f32_e32 v251, v181, v249
	v_exp_f32_e32 v244, v78
	v_exp_f32_e32 v245, v79
	v_add_f32_e32 v248, v182, v250
	v_add_f32_e32 v249, v183, v251
	v_exp_f32_e32 v246, v80
	v_mfma_f32_32x32x16_bf16 v[66:81], v[236:239], v[142:145], v[114:129]
	v_exp_f32_e32 v247, v193
	v_add_f32_e32 v248, v184, v248
	v_add_f32_e32 v249, v185, v249
	v_cvt_pk_bf16_f32 v98, v240, v241
	v_add_f32_e32 v250, v240, v248
	v_add_f32_e32 v251, v241, v249
	v_cvt_pk_bf16_f32 v99, v242, v243
	v_add_f32_e32 v250, v242, v250
	v_add_f32_e32 v251, v243, v251
	v_cvt_pk_bf16_f32 v100, v244, v245
	v_add_f32_e32 v250, v244, v250
	v_add_f32_e32 v251, v245, v251
	v_cvt_pk_bf16_f32 v101, v246, v247
	v_add_f32_e32 v156, v246, v250
	v_add_f32_e32 v157, v247, v251
	v_permlane32_swap_b32_e32 v98, v100
	v_permlane32_swap_b32_e32 v99, v101
	v_add_u32_e32 v0, s14, v161
	ds_read_b64_tr_b16 v[102:103], v0 offset:0
	ds_read_b64_tr_b16 v[104:105], v0 offset:0x800
	ds_read_b64_tr_b16 v[106:107], v0 offset:0x1000
	ds_read_b64_tr_b16 v[108:109], v0 offset:0x1800
	ds_read_b64_tr_b16 v[110:111], v0 offset:0x2000
	ds_read_b64_tr_b16 v[112:113], v0 offset:0x2800
	ds_read_b64_tr_b16 v[114:115], v0 offset:0x3000
	ds_read_b64_tr_b16 v[116:117], v0 offset:0x3800
	ds_read_b64_tr_b16 v[118:119], v0 offset:0x200
	ds_read_b64_tr_b16 v[120:121], v0 offset:0xa00
	ds_read_b64_tr_b16 v[122:123], v0 offset:0x1200
	ds_read_b64_tr_b16 v[124:125], v0 offset:0x1a00
	ds_read_b64_tr_b16 v[126:127], v0 offset:0x2200
	ds_read_b64_tr_b16 v[128:129], v0 offset:0x2a00
	ds_read_b64_tr_b16 v[174:175], v0 offset:0x3200
	ds_read_b64_tr_b16 v[176:177], v0 offset:0x3a00
	s_waitcnt lgkmcnt(8)
	s_nop 0
	v_mfma_f32_32x32x16_bf16 v[50:65], v[146:149], v[102:105], v[50:65]
	v_mfma_f32_32x32x16_bf16 v[50:65], v[150:153], v[106:109], v[50:65]
	v_mfma_f32_32x32x16_bf16 v[50:65], v[170:173], v[110:113], v[50:65]
	v_mfma_f32_32x32x16_bf16 v[50:65], v[98:101], v[114:117], v[50:65]
	ds_read_b64_tr_b16 v[102:103], v0 offset:0x400
	ds_read_b64_tr_b16 v[104:105], v0 offset:0xc00
	ds_read_b64_tr_b16 v[106:107], v0 offset:0x1400
	ds_read_b64_tr_b16 v[108:109], v0 offset:0x1c00
	ds_read_b64_tr_b16 v[110:111], v0 offset:0x2400
	ds_read_b64_tr_b16 v[112:113], v0 offset:0x2c00
	ds_read_b64_tr_b16 v[114:115], v0 offset:0x3400
	ds_read_b64_tr_b16 v[116:117], v0 offset:0x3c00
	s_waitcnt lgkmcnt(8)
	v_mfma_f32_32x32x16_bf16 v[34:49], v[146:149], v[118:121], v[34:49]
	v_mfma_f32_32x32x16_bf16 v[34:49], v[150:153], v[122:125], v[34:49]
	v_mfma_f32_32x32x16_bf16 v[34:49], v[170:173], v[126:129], v[34:49]
	v_mfma_f32_32x32x16_bf16 v[34:49], v[98:101], v[174:177], v[34:49]
	ds_read_b64_tr_b16 v[118:119], v0 offset:0x600
	ds_read_b64_tr_b16 v[120:121], v0 offset:0xe00
	ds_read_b64_tr_b16 v[122:123], v0 offset:0x1600
	ds_read_b64_tr_b16 v[124:125], v0 offset:0x1e00
	ds_read_b64_tr_b16 v[126:127], v0 offset:0x2600
	ds_read_b64_tr_b16 v[128:129], v0 offset:0x2e00
	ds_read_b64_tr_b16 v[174:175], v0 offset:0x3600
	ds_read_b64_tr_b16 v[176:177], v0 offset:0x3e00
	s_waitcnt lgkmcnt(8)
	v_mfma_f32_32x32x16_bf16 v[18:33], v[146:149], v[102:105], v[18:33]
	v_mfma_f32_32x32x16_bf16 v[18:33], v[150:153], v[106:109], v[18:33]
	v_mfma_f32_32x32x16_bf16 v[18:33], v[170:173], v[110:113], v[18:33]
	v_mfma_f32_32x32x16_bf16 v[18:33], v[98:101], v[114:117], v[18:33]
	s_waitcnt lgkmcnt(0)
	v_mfma_f32_32x32x16_bf16 v[2:17], v[146:149], v[118:121], v[2:17]
	s_waitcnt vmcnt(4)
	s_barrier
	s_add_i32 s13, s13, -1
	s_cmp_lg_u32 s13, 0
	s_mov_b32 s2, s12
	s_mov_b32 s14, s63
	v_mfma_f32_32x32x16_bf16 v[2:17], v[150:153], v[122:125], v[2:17]
	v_mfma_f32_32x32x16_bf16 v[2:17], v[170:173], v[126:129], v[2:17]
	v_mfma_f32_32x32x16_bf16 v[2:17], v[98:101], v[174:177], v[2:17]
	s_cbranch_scc1 .LBB0_821
	s_branch .LBB0_823

.LBB0_969:
	s_cmp_lt_i32 s83, s7
	s_cselect_b64 s[18:19], -1, 0
	s_and_b64 s[34:35], s[18:19], exec
	s_cselect_b32 s2, 0x98000, 0
	s_cmp_lg_u64 s[18:19], 0
	v_add_u32_e32 v186, s2, v186
	v_add_u32_e32 v187, s2, v187
	s_addc_u32 s83, s83, 0
	v_lshl_add_u32 v181, s57, 14, v15
	v_lshl_add_u32 v213, s13, 8, v212
	v_add_u32_e32 v10, v181, v188
	ds_read_b128 v[2:5], v213
	ds_read_b128 v[6:9], v10
	ds_read_b128 v[10:13], v10 offset:8192
	s_waitcnt lgkmcnt(0)
	v_mfma_f32_32x32x16_bf16 v[112:127], v[6:9], v[144:147], 0
	v_sub_f32_e32 v2, v180, v2
	v_sub_f32_e32 v3, v180, v3
	v_sub_f32_e32 v4, v180, v4
	v_sub_f32_e32 v5, v180, v5
	v_fmac_f32_e32 v2, 0x3e0293ee, v96
	v_fmac_f32_e32 v3, 0x3e0293ee, v97
	v_fmac_f32_e32 v4, 0x3e0293ee, v98
	v_fmac_f32_e32 v5, 0x3e0293ee, v99
	v_exp_f32_e32 v214, v2
	v_exp_f32_e32 v215, v3
	v_exp_f32_e32 v222, v4
	v_exp_f32_e32 v223, v5
	v_mfma_f32_32x32x16_bf16 v[128:143], v[10:13], v[144:147], 0
	ds_read_b128 v[2:5], v213 offset:32
	v_add_u32_e32 v10, v181, v189
	ds_read_b128 v[6:9], v10
	ds_read_b128 v[10:13], v10 offset:8192
	s_waitcnt lgkmcnt(0)
	v_mfma_f32_32x32x16_bf16 v[128:143], v[10:13], v[148:151], v[128:143]
	v_sub_f32_e32 v2, v180, v2
	v_sub_f32_e32 v3, v180, v3
	v_sub_f32_e32 v4, v180, v4
	v_sub_f32_e32 v5, v180, v5
	v_fmac_f32_e32 v2, 0x3e0293ee, v100
	v_fmac_f32_e32 v3, 0x3e0293ee, v101
	v_fmac_f32_e32 v4, 0x3e0293ee, v102
	v_fmac_f32_e32 v5, 0x3e0293ee, v103
	v_exp_f32_e32 v100, v2
	v_exp_f32_e32 v101, v3
	v_exp_f32_e32 v102, v4
	v_exp_f32_e32 v103, v5
	v_cvt_pk_bf16_f32 v2, v214, v215
	v_cvt_pk_bf16_f32 v3, v222, v223
	v_cvt_pk_bf16_f32 v4, v100, v101
	v_cvt_pk_bf16_f32 v5, v102, v103
	s_nop 0
	v_permlane32_swap_b32_e32 v2, v4
	v_permlane32_swap_b32_e32 v3, v5
	v_mfma_f32_32x32x16_bf16 v[112:127], v[6:9], v[148:151], v[112:127]
	ds_read_b128 v[6:9], v213 offset:64
	v_add_u32_e32 v96, v181, v190
	ds_read_b128 v[10:13], v96
	ds_read_b128 v[96:99], v96 offset:8192
	s_waitcnt lgkmcnt(0)
	v_mfma_f32_32x32x16_bf16 v[112:127], v[10:13], v[152:155], v[112:127]
	v_sub_f32_e32 v6, v180, v6
	v_sub_f32_e32 v7, v180, v7
	v_fmac_f32_e32 v6, 0x3e0293ee, v104
	v_fmac_f32_e32 v7, 0x3e0293ee, v105
	v_sub_f32_e32 v8, v180, v8
	v_sub_f32_e32 v9, v180, v9
	v_fmac_f32_e32 v8, 0x3e0293ee, v106
	v_fmac_f32_e32 v9, 0x3e0293ee, v107
	v_exp_f32_e32 v104, v6
	v_exp_f32_e32 v105, v7
	v_add_f32_e32 v6, v182, v214
	v_add_f32_e32 v7, v183, v215
	v_exp_f32_e32 v182, v8
	v_add_f32_e32 v6, v222, v6
	v_add_f32_e32 v7, v223, v7
	v_exp_f32_e32 v183, v9
	v_add_f32_e32 v6, v6, v100
	v_add_f32_e32 v7, v7, v101
	v_mfma_f32_32x32x16_bf16 v[128:143], v[96:99], v[152:155], v[128:143]
	v_add_f32_e64 v6, v102, v6
	v_add_f32_e64 v7, v103, v7
	v_add_f32_e64 v106, v6, v104
	v_add_f32_e64 v107, v7, v105
	ds_read_b128 v[6:9], v213 offset:96
	v_add_u32_e32 v96, v181, v191
	ds_read_b128 v[10:13], v96
	ds_read_b128 v[96:99], v96 offset:8192
	s_waitcnt lgkmcnt(0)
	v_mfma_f32_32x32x16_bf16 v[128:143], v[96:99], v[156:159], v[128:143]
	v_sub_f32_e32 v6, v180, v6
	v_sub_f32_e32 v7, v180, v7
	v_sub_f32_e32 v8, v180, v8
	v_sub_f32_e32 v9, v180, v9
	v_fmac_f32_e32 v6, 0x3e0293ee, v108
	v_fmac_f32_e32 v7, 0x3e0293ee, v109
	v_fmac_f32_e32 v8, 0x3e0293ee, v110
	v_fmac_f32_e32 v9, 0x3e0293ee, v111
	v_exp_f32_e32 v108, v6
	v_exp_f32_e32 v109, v7
	v_exp_f32_e32 v110, v8
	v_exp_f32_e32 v111, v9
	v_cvt_pk_bf16_f32 v6, v104, v105
	v_cvt_pk_bf16_f32 v7, v182, v183
	v_cvt_pk_bf16_f32 v8, v108, v109
	v_cvt_pk_bf16_f32 v9, v110, v111
	s_nop 0
	v_permlane32_swap_b32_e32 v6, v8
	v_permlane32_swap_b32_e32 v7, v9
	v_mfma_f32_32x32x16_bf16 v[112:127], v[10:13], v[156:159], v[112:127]
	v_add_u32_e32 v100, v181, v192
	ds_read_b128 v[10:13], v213 offset:128
	ds_read_b128 v[96:99], v100
	ds_read_b128 v[100:103], v100 offset:8192
	s_waitcnt lgkmcnt(0)
	v_mfma_f32_32x32x16_bf16 v[112:127], v[96:99], v[160:163], v[112:127]
	v_sub_f32_e32 v10, v180, v10
	v_sub_f32_e32 v11, v180, v11
	v_fmac_f32_e32 v10, 0x3e0293ee, v80
	v_fmac_f32_e32 v11, 0x3e0293ee, v81
	v_exp_f32_e32 v104, v10
	v_exp_f32_e32 v105, v11
	v_sub_f32_e32 v12, v180, v12
	v_sub_f32_e32 v13, v180, v13
	v_fmac_f32_e32 v12, 0x3e0293ee, v82
	v_fmac_f32_e32 v13, 0x3e0293ee, v83
	v_exp_f32_e32 v214, v12
	v_exp_f32_e32 v215, v13
	v_mfma_f32_32x32x16_bf16 v[128:143], v[100:103], v[160:163], v[128:143]
	ds_read_b128 v[10:13], v213 offset:160
	v_add_u32_e32 v96, v181, v193
	ds_read_b128 v[80:83], v96
	ds_read_b128 v[96:99], v96 offset:8192
	s_waitcnt lgkmcnt(0)
	v_mfma_f32_32x32x16_bf16 v[128:143], v[96:99], v[164:167], v[128:143]
	v_sub_f32_e32 v10, v180, v10
	v_sub_f32_e32 v11, v180, v11
	v_sub_f32_e32 v12, v180, v12
	v_sub_f32_e32 v13, v180, v13
	v_fmac_f32_e32 v10, 0x3e0293ee, v84
	v_fmac_f32_e32 v11, 0x3e0293ee, v85
	v_fmac_f32_e32 v12, 0x3e0293ee, v86
	v_fmac_f32_e32 v13, 0x3e0293ee, v87
	v_exp_f32_e32 v100, v10
	v_exp_f32_e32 v101, v11
	v_exp_f32_e32 v102, v12
	v_exp_f32_e32 v103, v13
	v_cvt_pk_bf16_f32 v10, v104, v105
	v_cvt_pk_bf16_f32 v11, v214, v215
	v_cvt_pk_bf16_f32 v12, v100, v101
	v_cvt_pk_bf16_f32 v13, v102, v103
	s_nop 0
	v_permlane32_swap_b32_e32 v10, v12
	v_permlane32_swap_b32_e32 v11, v13
	v_mfma_f32_32x32x16_bf16 v[112:127], v[80:83], v[164:167], v[112:127]
	v_add_u32_e32 v96, v181, v194
	ds_read_b128 v[80:83], v213 offset:192
	ds_read_b128 v[84:87], v96
	ds_read_b128 v[96:99], v96 offset:8192
	s_waitcnt lgkmcnt(0)
; #define SBAR() __builtin_amdgcn_sched_barrier(0)
; #define VSET(S, d0) do { constexpr int b_ = (d0) * 512; TRRD(S##l0, b_); TRRD(S##h0, b_ + 2048); TRRD(S##l1, b_ + 4096); TRRD(S##h1, b_ + 6144); \
;         TRRD(S##l2, b_ + 8192); TRRD(S##h2, b_ + 10240); TRRD(S##l3, b_ + 12288); TRRD(S##h3, b_ + 14336); } while (0)
; #define LWAIT(n) do { asm volatile("s_waitcnt lgkmcnt(" #n ")" ::: "memory"); SBAR(); } while (0)
; __device__ __forceinline__ void pv_tile(f32x16* o, unsigned vb, bf16x8 pa0, bf16x8 pa1, bf16x8 pa2, bf16x8 pa3) {
;     ...
;     s16x4 Al0, Al1, Al2, Al3, Ah0, Ah1, Ah2, Ah3, Bl0, Bl1, Bl2, Bl3, Bh0, Bh1, Bh2, Bh3;
;     VSET(A, 0);
;     VSET(B, 1); LWAIT(8); VMMA(A, 0); SBAR();
;     VSET(A, 2); LWAIT(8); VMMA(B, 1); SBAR();
;     VSET(B, 3); LWAIT(8); VMMA(A, 2); SBAR();
;     LWAIT(0); VMMA(B, 3);
	v_mfma_f32_32x32x16_bf16 v[112:127], v[84:87], v[168:171], v[112:127]
	v_sub_f32_e32 v80, v180, v80
	v_sub_f32_e32 v81, v180, v81
	v_sub_f32_e32 v82, v180, v82
	v_sub_f32_e32 v83, v180, v83
	v_fmac_f32_e32 v80, 0x3e0293ee, v88
	v_fmac_f32_e32 v81, 0x3e0293ee, v89
	v_fmac_f32_e32 v82, 0x3e0293ee, v90
	v_fmac_f32_e32 v83, 0x3e0293ee, v91
	v_exp_f32_e32 v88, v80
	v_exp_f32_e32 v89, v81
	v_exp_f32_e32 v90, v82
	v_exp_f32_e32 v91, v83
	v_mfma_f32_32x32x16_bf16 v[128:143], v[96:99], v[168:171], v[128:143]
	ds_read_b128 v[80:83], v213 offset:224
	v_add_u32_e32 v96, v181, v195
	ds_read_b128 v[84:87], v96
	ds_read_b128 v[232:235], v96 offset:8192
	v_cvt_pk_bf16_f32 v236, v88, v89
	v_cvt_pk_bf16_f32 v237, v90, v91
	s_waitcnt lgkmcnt(0)
	v_sub_f32_e32 v80, v180, v80
	v_sub_f32_e32 v81, v180, v81
	v_fmac_f32_e32 v80, 0x3e0293ee, v92
	v_fmac_f32_e32 v81, 0x3e0293ee, v93
	v_add_f32_e32 v92, v182, v106
	v_add_f32_e32 v93, v183, v107
	v_sub_f32_e32 v82, v180, v82
	v_add_f32_e32 v92, v92, v108
	v_add_f32_e32 v93, v93, v109
	v_sub_f32_e32 v83, v180, v83
	v_add_f32_e32 v92, v110, v92
	v_add_f32_e32 v93, v111, v93
	v_fmac_f32_e32 v82, 0x3e0293ee, v94
	v_add_f32_e32 v92, v92, v104
	v_add_f32_e32 v93, v93, v105
	v_fmac_f32_e32 v83, 0x3e0293ee, v95
	v_add_f32_e32 v92, v214, v92
	v_add_f32_e32 v93, v215, v93
	v_exp_f32_e32 v80, v80
	v_exp_f32_e32 v81, v81
	v_add_f32_e32 v92, v92, v100
	v_add_f32_e32 v93, v93, v101
	v_exp_f32_e32 v82, v82
	v_exp_f32_e32 v83, v83
	v_add_f32_e32 v92, v102, v92
	v_add_f32_e32 v93, v103, v93
	v_add_f32_e32 v92, v92, v88
	v_add_f32_e32 v93, v93, v89
	v_add_f32_e32 v92, v90, v92
	v_add_f32_e32 v93, v91, v93
	v_add_f32_e32 v92, v92, v80
	v_add_f32_e32 v93, v93, v81
	v_add_f32_e32 v182, v82, v92
	v_add_f32_e32 v183, v83, v93
	v_cvt_pk_bf16_f32 v238, v80, v81
	v_mfma_f32_32x32x16_bf16 v[96:111], v[84:87], v[172:175], v[112:127]
	v_cvt_pk_bf16_f32 v239, v82, v83
	v_permlane32_swap_b32_e32 v236, v238
	v_mfma_f32_32x32x16_bf16 v[80:95], v[232:235], v[172:175], v[128:143]
	v_permlane32_swap_b32_e32 v237, v239
	v_add_u32_e32 v181, s15, v179
	ds_read_b64_tr_b16 v[112:113], v181 offset:0
	ds_read_b64_tr_b16 v[114:115], v181 offset:0x800
	ds_read_b64_tr_b16 v[116:117], v181 offset:0x1000
	ds_read_b64_tr_b16 v[118:119], v181 offset:0x1800
	ds_read_b64_tr_b16 v[120:121], v181 offset:0x2000
	ds_read_b64_tr_b16 v[122:123], v181 offset:0x2800
	ds_read_b64_tr_b16 v[124:125], v181 offset:0x3000
	ds_read_b64_tr_b16 v[126:127], v181 offset:0x3800
	ds_read_b64_tr_b16 v[128:129], v181 offset:0x200
	ds_read_b64_tr_b16 v[130:131], v181 offset:0xa00
	ds_read_b64_tr_b16 v[132:133], v181 offset:0x1200
	ds_read_b64_tr_b16 v[134:135], v181 offset:0x1a00
	ds_read_b64_tr_b16 v[136:137], v181 offset:0x2200
	ds_read_b64_tr_b16 v[138:139], v181 offset:0x2a00
	ds_read_b64_tr_b16 v[140:141], v181 offset:0x3200
	ds_read_b64_tr_b16 v[142:143], v181 offset:0x3a00
	s_waitcnt lgkmcnt(8)
	s_nop 0
	v_mfma_f32_32x32x16_bf16 v[64:79], v[2:5], v[112:115], v[64:79]
	v_mfma_f32_32x32x16_bf16 v[64:79], v[6:9], v[116:119], v[64:79]
	v_mfma_f32_32x32x16_bf16 v[64:79], v[10:13], v[120:123], v[64:79]
	v_mfma_f32_32x32x16_bf16 v[64:79], v[236:239], v[124:127], v[64:79]
	ds_read_b64_tr_b16 v[112:113], v181 offset:0x400
	ds_read_b64_tr_b16 v[114:115], v181 offset:0xc00
	ds_read_b64_tr_b16 v[116:117], v181 offset:0x1400
	ds_read_b64_tr_b16 v[118:119], v181 offset:0x1c00
	ds_read_b64_tr_b16 v[120:121], v181 offset:0x2400
	ds_read_b64_tr_b16 v[122:123], v181 offset:0x2c00
	ds_read_b64_tr_b16 v[124:125], v181 offset:0x3400
	ds_read_b64_tr_b16 v[126:127], v181 offset:0x3c00
	s_waitcnt lgkmcnt(8)
	v_mfma_f32_32x32x16_bf16 v[48:63], v[2:5], v[128:131], v[48:63]
	v_mfma_f32_32x32x16_bf16 v[48:63], v[6:9], v[132:135], v[48:63]
	v_mfma_f32_32x32x16_bf16 v[48:63], v[10:13], v[136:139], v[48:63]
	v_mfma_f32_32x32x16_bf16 v[48:63], v[236:239], v[140:143], v[48:63]
	ds_read_b64_tr_b16 v[128:129], v181 offset:0x600
	ds_read_b64_tr_b16 v[130:131], v181 offset:0xe00
	ds_read_b64_tr_b16 v[132:133], v181 offset:0x1600
	ds_read_b64_tr_b16 v[134:135], v181 offset:0x1e00
	ds_read_b64_tr_b16 v[136:137], v181 offset:0x2600
	ds_read_b64_tr_b16 v[138:139], v181 offset:0x2e00
	ds_read_b64_tr_b16 v[140:141], v181 offset:0x3600
	ds_read_b64_tr_b16 v[142:143], v181 offset:0x3e00
	s_waitcnt lgkmcnt(8)
	v_mfma_f32_32x32x16_bf16 v[32:47], v[2:5], v[112:115], v[32:47]
	v_mfma_f32_32x32x16_bf16 v[32:47], v[6:9], v[116:119], v[32:47]
	v_mfma_f32_32x32x16_bf16 v[32:47], v[10:13], v[120:123], v[32:47]
	v_mfma_f32_32x32x16_bf16 v[32:47], v[236:239], v[124:127], v[32:47]
	s_waitcnt lgkmcnt(0)
	v_mfma_f32_32x32x16_bf16 v[16:31], v[2:5], v[128:131], v[16:31]
	s_waitcnt vmcnt(5)
	s_barrier
	s_add_i32 s6, s6, 1
	s_cmp_ge_i32 s6, s8
	s_mov_b32 s15, s57
	s_mov_b32 s57, s63
	v_mfma_f32_32x32x16_bf16 v[16:31], v[6:9], v[132:135], v[16:31]
	s_mov_b32 s63, s13
	v_mfma_f32_32x32x16_bf16 v[16:31], v[10:13], v[136:139], v[16:31]
	v_mfma_f32_32x32x16_bf16 v[16:31], v[236:239], v[140:143], v[16:31]
	s_cbranch_scc1 .LBB0_973
